# MB=4 K-loops: the B0 fragment reads of P1/P5 are issued one MFMA block earlier, interleaved in the shadow of M8/M4 (their registers are free there), shortening the two heaviest loader segments
# speedup vs baseline: 1.0038x; 1.0009x over previous
.LBB0_156:
	s_ashr_i32 s65, s64, 31
	s_lshl_b64 s[34:35], s[64:65], 20
	s_add_u32 s66, s33, s34
	s_addc_u32 s67, s38, s35
	s_and_b64 s[34:35], s[72:73], exec
	s_cselect_b32 s2, s67, s9
	s_cselect_b32 s13, s66, s8
	s_ashr_i32 s63, s62, 31
	s_lshl_b64 s[34:35], s[62:63], 20
	s_add_u32 s68, s36, s34
	s_addc_u32 s69, s37, s35
	s_and_b64 s[34:35], s[72:73], exec
	s_cselect_b32 s20, s69, s11
	s_cselect_b32 s63, s68, s10
	s_add_u32 s8, s8, 0x80080
	s_addc_u32 s9, s9, 0
	s_add_u32 s65, s10, 0x100
	v_mov_b32_e32 v0, 0
	s_addc_u32 s71, s11, 0
	s_mov_b32 s74, -2
	v_mov_b32_e32 v1, v0
	v_mov_b32_e32 v2, v0
	v_mov_b32_e32 v3, v0
	v_mov_b32_e32 v4, v0
	v_mov_b32_e32 v5, v0
	v_mov_b32_e32 v6, v0
	v_mov_b32_e32 v7, v0
	v_mov_b32_e32 v16, v0
	v_mov_b32_e32 v17, v0
	v_mov_b32_e32 v18, v0
	v_mov_b32_e32 v19, v0
	v_mov_b32_e32 v20, v0
	v_mov_b32_e32 v21, v0
	v_mov_b32_e32 v22, v0
	v_mov_b32_e32 v23, v0
	v_mov_b32_e32 v32, v0
	v_mov_b32_e32 v33, v0
	v_mov_b32_e32 v34, v0
	v_mov_b32_e32 v35, v0
	v_mov_b32_e32 v36, v0
	v_mov_b32_e32 v37, v0
	v_mov_b32_e32 v38, v0
	v_mov_b32_e32 v39, v0
	v_mov_b32_e32 v48, v0
	v_mov_b32_e32 v49, v0
	v_mov_b32_e32 v50, v0
	v_mov_b32_e32 v51, v0
	v_mov_b32_e32 v52, v0
	v_mov_b32_e32 v53, v0
	v_mov_b32_e32 v54, v0
	v_mov_b32_e32 v55, v0
	v_mov_b32_e32 v8, v0
	v_mov_b32_e32 v9, v0
	v_mov_b32_e32 v10, v0
	v_mov_b32_e32 v11, v0
	v_mov_b32_e32 v12, v0
	v_mov_b32_e32 v13, v0
	v_mov_b32_e32 v14, v0
	v_mov_b32_e32 v15, v0
	v_mov_b32_e32 v24, v0
	v_mov_b32_e32 v25, v0
	v_mov_b32_e32 v26, v0
	v_mov_b32_e32 v27, v0
	v_mov_b32_e32 v28, v0
	v_mov_b32_e32 v29, v0
	v_mov_b32_e32 v30, v0
	v_mov_b32_e32 v31, v0
	v_mov_b32_e32 v40, v0
	v_mov_b32_e32 v41, v0
	v_mov_b32_e32 v42, v0
	v_mov_b32_e32 v43, v0
	v_mov_b32_e32 v44, v0
	v_mov_b32_e32 v45, v0
	v_mov_b32_e32 v46, v0
	v_mov_b32_e32 v47, v0
	v_mov_b32_e32 v56, v0
	v_mov_b32_e32 v57, v0
	v_mov_b32_e32 v58, v0
	v_mov_b32_e32 v59, v0
	v_mov_b32_e32 v60, v0
	v_mov_b32_e32 v61, v0
	v_mov_b32_e32 v62, v0
	v_mov_b32_e32 v63, v0
	v_mov_b32_e32 v64, v0
	v_mov_b32_e32 v65, v0
	v_mov_b32_e32 v66, v0
	v_mov_b32_e32 v67, v0
	v_mov_b32_e32 v68, v0
	v_mov_b32_e32 v69, v0
	v_mov_b32_e32 v70, v0
	v_mov_b32_e32 v71, v0
	v_mov_b32_e32 v80, v0
	v_mov_b32_e32 v81, v0
	v_mov_b32_e32 v82, v0
	v_mov_b32_e32 v83, v0
	v_mov_b32_e32 v84, v0
	v_mov_b32_e32 v85, v0
	v_mov_b32_e32 v86, v0
	v_mov_b32_e32 v87, v0
	v_mov_b32_e32 v96, v0
	v_mov_b32_e32 v97, v0
	v_mov_b32_e32 v98, v0
	v_mov_b32_e32 v99, v0
	v_mov_b32_e32 v100, v0
	v_mov_b32_e32 v101, v0
	v_mov_b32_e32 v102, v0
	v_mov_b32_e32 v103, v0
	v_mov_b32_e32 v112, v0
	v_mov_b32_e32 v113, v0
	v_mov_b32_e32 v114, v0
	v_mov_b32_e32 v115, v0
	v_mov_b32_e32 v116, v0
	v_mov_b32_e32 v117, v0
	v_mov_b32_e32 v118, v0
	v_mov_b32_e32 v119, v0
	v_mov_b32_e32 v72, v0
	v_mov_b32_e32 v73, v0
	v_mov_b32_e32 v74, v0
	v_mov_b32_e32 v75, v0
	v_mov_b32_e32 v76, v0
	v_mov_b32_e32 v77, v0
	v_mov_b32_e32 v78, v0
	v_mov_b32_e32 v79, v0
	v_mov_b32_e32 v88, v0
	v_mov_b32_e32 v89, v0
	v_mov_b32_e32 v90, v0
	v_mov_b32_e32 v91, v0
	v_mov_b32_e32 v92, v0
	v_mov_b32_e32 v93, v0
	v_mov_b32_e32 v94, v0
	v_mov_b32_e32 v95, v0
	v_mov_b32_e32 v104, v0
	v_mov_b32_e32 v105, v0
	v_mov_b32_e32 v106, v0
	v_mov_b32_e32 v107, v0
	v_mov_b32_e32 v108, v0
	v_mov_b32_e32 v109, v0
	v_mov_b32_e32 v110, v0
	v_mov_b32_e32 v111, v0
	v_mov_b32_e32 v120, v0
	v_mov_b32_e32 v121, v0
	v_mov_b32_e32 v122, v0
	v_mov_b32_e32 v123, v0
	v_mov_b32_e32 v124, v0
	v_mov_b32_e32 v125, v0
	v_mov_b32_e32 v126, v0
	v_mov_b32_e32 v127, v0
	v_add_u32_e32 v140, s91, v180
	ds_read_b128 v[128:131], v140
	ds_read_b128 v[132:135], v140 offset:1024
	ds_read_b128 v[136:139], v140 offset:2048
	ds_read_b128 v[140:143], v140 offset:3072
	.p2align 7
.LBB0_157:
	s_add_u32 s10, s8, 0xfff80080
	s_addc_u32 s11, s9, -1
	s_cmp_eq_u32 s74, 28
	s_cselect_b32 s73, s2, s11
	s_cselect_b32 s72, s13, s10
	s_cselect_b32 s11, s20, s71
	s_cselect_b32 s10, s63, s65
	s_add_i32 m0, s40, 0xc000
	ds_read_b128 v[144:147], v208
	ds_read_b128 v[172:175], v208 offset:1024
	ds_read_b128 v[176:179], v208 offset:2048
	ds_read_b128 v[212:215], v208 offset:3072
	global_load_lds_dwordx4 v166, s[8:9]
	s_add_i32 m0, s40, 0xe000
	ds_read_b128 v[216:219], v208 offset:4096
	ds_read_b128 v[220:223], v208 offset:5120
	ds_read_b128 v[224:227], v208 offset:6144
	ds_read_b128 v[228:231], v208 offset:7168
	global_load_lds_dwordx4 v168, s[8:9]
	s_waitcnt lgkmcnt(8)
	s_barrier
	s_waitcnt lgkmcnt(0)
	v_mfma_f32_16x16x32_bf16 v[124:127], v[128:131], v[144:147], v[124:127]
	v_mfma_f32_16x16x32_bf16 v[120:123], v[136:139], v[144:147], v[120:123]
	v_mfma_f32_16x16x32_bf16 v[108:111], v[128:131], v[176:179], v[108:111]
	v_mfma_f32_16x16x32_bf16 v[104:107], v[136:139], v[176:179], v[104:107]
	v_mfma_f32_16x16x32_bf16 v[92:95], v[128:131], v[216:219], v[92:95]
	v_mfma_f32_16x16x32_bf16 v[88:91], v[136:139], v[216:219], v[88:91]
	v_mfma_f32_16x16x32_bf16 v[76:79], v[128:131], v[224:227], v[76:79]
	v_mfma_f32_16x16x32_bf16 v[72:75], v[136:139], v[224:227], v[72:75]
	v_mfma_f32_16x16x32_bf16 v[124:127], v[132:135], v[172:175], v[124:127]
	v_mfma_f32_16x16x32_bf16 v[120:123], v[140:143], v[172:175], v[120:123]
	v_mfma_f32_16x16x32_bf16 v[108:111], v[132:135], v[212:215], v[108:111]
	v_mfma_f32_16x16x32_bf16 v[104:107], v[140:143], v[212:215], v[104:107]
	v_mfma_f32_16x16x32_bf16 v[92:95], v[132:135], v[220:223], v[92:95]
	v_mfma_f32_16x16x32_bf16 v[88:91], v[140:143], v[220:223], v[88:91]
	v_mfma_f32_16x16x32_bf16 v[76:79], v[132:135], v[228:231], v[76:79]
	v_mfma_f32_16x16x32_bf16 v[72:75], v[140:143], v[228:231], v[72:75]
	s_barrier
	v_add_u32_e32 v156, s92, v180
	s_add_i32 m0, s40, 0x10000
	ds_read_b128 v[232:235], v156
	ds_read_b128 v[236:239], v156 offset:1024
	global_load_lds_dwordx4 v150, s[10:11]
	s_add_i32 m0, s40, 0x12000
	ds_read_b128 v[240:243], v156 offset:2048
	ds_read_b128 v[244:247], v156 offset:3072
	global_load_lds_dwordx4 v154, s[10:11]
	s_barrier
	s_waitcnt lgkmcnt(0)
	v_mfma_f32_16x16x32_bf16 v[116:119], v[232:235], v[144:147], v[116:119]
	v_mfma_f32_16x16x32_bf16 v[112:115], v[240:243], v[144:147], v[112:115]
	v_mfma_f32_16x16x32_bf16 v[100:103], v[232:235], v[176:179], v[100:103]
	v_mfma_f32_16x16x32_bf16 v[96:99], v[240:243], v[176:179], v[96:99]
	v_mfma_f32_16x16x32_bf16 v[84:87], v[232:235], v[216:219], v[84:87]
	v_mfma_f32_16x16x32_bf16 v[80:83], v[240:243], v[216:219], v[80:83]
	v_mfma_f32_16x16x32_bf16 v[68:71], v[232:235], v[224:227], v[68:71]
	v_mfma_f32_16x16x32_bf16 v[64:67], v[240:243], v[224:227], v[64:67]
	v_mfma_f32_16x16x32_bf16 v[116:119], v[236:239], v[172:175], v[116:119]
	v_mfma_f32_16x16x32_bf16 v[112:115], v[244:247], v[172:175], v[112:115]
	v_mfma_f32_16x16x32_bf16 v[100:103], v[236:239], v[212:215], v[100:103]
	v_mfma_f32_16x16x32_bf16 v[96:99], v[244:247], v[212:215], v[96:99]
	v_mfma_f32_16x16x32_bf16 v[84:87], v[236:239], v[220:223], v[84:87]
	v_mfma_f32_16x16x32_bf16 v[80:83], v[244:247], v[220:223], v[80:83]
	v_mfma_f32_16x16x32_bf16 v[68:71], v[236:239], v[228:231], v[68:71]
	v_mfma_f32_16x16x32_bf16 v[64:67], v[244:247], v[228:231], v[64:67]
	s_barrier
	s_mov_b32 m0, s40
	ds_read_b128 v[144:147], v208 offset:16384
	ds_read_b128 v[172:175], v208 offset:17408
	ds_read_b128 v[176:179], v208 offset:18432
	ds_read_b128 v[212:215], v208 offset:19456
	global_load_lds_dwordx4 v148, s[72:73]
	s_mov_b32 m0, s41
	ds_read_b128 v[216:219], v208 offset:20480
	ds_read_b128 v[220:223], v208 offset:21504
	ds_read_b128 v[224:227], v208 offset:22528
	ds_read_b128 v[228:231], v208 offset:23552
	global_load_lds_dwordx4 v152, s[72:73]
	s_barrier
	s_waitcnt lgkmcnt(0)
	v_mfma_f32_16x16x32_bf16 v[60:63], v[128:131], v[144:147], v[60:63]
	v_mfma_f32_16x16x32_bf16 v[56:59], v[136:139], v[144:147], v[56:59]
	v_mfma_f32_16x16x32_bf16 v[44:47], v[128:131], v[176:179], v[44:47]
	v_mfma_f32_16x16x32_bf16 v[40:43], v[136:139], v[176:179], v[40:43]
	v_mfma_f32_16x16x32_bf16 v[28:31], v[128:131], v[216:219], v[28:31]
	v_mfma_f32_16x16x32_bf16 v[24:27], v[136:139], v[216:219], v[24:27]
	v_mfma_f32_16x16x32_bf16 v[12:15], v[128:131], v[224:227], v[12:15]
	v_mfma_f32_16x16x32_bf16 v[8:11], v[136:139], v[224:227], v[8:11]
	v_mfma_f32_16x16x32_bf16 v[60:63], v[132:135], v[172:175], v[60:63]
	v_mfma_f32_16x16x32_bf16 v[56:59], v[140:143], v[172:175], v[56:59]
	v_mfma_f32_16x16x32_bf16 v[44:47], v[132:135], v[212:215], v[44:47]
	v_mfma_f32_16x16x32_bf16 v[40:43], v[140:143], v[212:215], v[40:43]
	v_mfma_f32_16x16x32_bf16 v[28:31], v[132:135], v[220:223], v[28:31]
	v_mfma_f32_16x16x32_bf16 v[24:27], v[140:143], v[220:223], v[24:27]
	v_mfma_f32_16x16x32_bf16 v[12:15], v[132:135], v[228:231], v[12:15]
	v_mfma_f32_16x16x32_bf16 v[8:11], v[140:143], v[228:231], v[8:11]
	s_barrier
	s_add_u32 s34, s10, 0x80000
	s_addc_u32 s35, s11, 0
	s_add_i32 m0, s40, 0x14000
	s_nop 0
	global_load_lds_dwordx4 v150, s[34:35]
	s_add_i32 m0, s40, 0x16000
	s_nop 0
	global_load_lds_dwordx4 v154, s[34:35]
	s_waitcnt vmcnt(6)
	s_barrier
	v_mfma_f32_16x16x32_bf16 v[52:55], v[232:235], v[144:147], v[52:55]
	v_mfma_f32_16x16x32_bf16 v[48:51], v[240:243], v[144:147], v[48:51]
	v_mfma_f32_16x16x32_bf16 v[36:39], v[232:235], v[176:179], v[36:39]
	v_mfma_f32_16x16x32_bf16 v[32:35], v[240:243], v[176:179], v[32:35]
	s_add_i32 s75, 0, 0x18000
	v_mfma_f32_16x16x32_bf16 v[20:23], v[232:235], v[216:219], v[20:23]
	v_mfma_f32_16x16x32_bf16 v[16:19], v[240:243], v[216:219], v[16:19]
	v_add_u32_e32 v140, s75, v180
	v_mfma_f32_16x16x32_bf16 v[4:7], v[232:235], v[224:227], v[4:7]
	v_mfma_f32_16x16x32_bf16 v[0:3], v[240:243], v[224:227], v[0:3]
	ds_read_b128 v[128:131], v140
	v_mfma_f32_16x16x32_bf16 v[52:55], v[236:239], v[172:175], v[52:55]
	v_mfma_f32_16x16x32_bf16 v[48:51], v[244:247], v[172:175], v[48:51]
	ds_read_b128 v[132:135], v140 offset:1024
	v_mfma_f32_16x16x32_bf16 v[36:39], v[236:239], v[212:215], v[36:39]
	v_mfma_f32_16x16x32_bf16 v[32:35], v[244:247], v[212:215], v[32:35]
	ds_read_b128 v[136:139], v140 offset:2048
	v_mfma_f32_16x16x32_bf16 v[20:23], v[236:239], v[220:223], v[20:23]
	v_mfma_f32_16x16x32_bf16 v[16:19], v[244:247], v[220:223], v[16:19]
	ds_read_b128 v[140:143], v140 offset:3072
	v_mfma_f32_16x16x32_bf16 v[4:7], v[236:239], v[228:231], v[4:7]
	v_mfma_f32_16x16x32_bf16 v[0:3], v[244:247], v[228:231], v[0:3]
	s_barrier
	s_add_u32 s34, s72, 0x80000
	s_addc_u32 s35, s73, 0
	s_mov_b32 m0, s82
	ds_read_b128 v[144:147], v208 offset:32768
	ds_read_b128 v[172:175], v208 offset:33792
	ds_read_b128 v[176:179], v208 offset:34816
	ds_read_b128 v[212:215], v208 offset:35840
	global_load_lds_dwordx4 v148, s[34:35]
	s_mov_b32 m0, s83
	ds_read_b128 v[216:219], v208 offset:36864
	ds_read_b128 v[220:223], v208 offset:37888
	ds_read_b128 v[224:227], v208 offset:38912
	ds_read_b128 v[228:231], v208 offset:39936
	global_load_lds_dwordx4 v152, s[34:35]
	s_waitcnt lgkmcnt(8)
	s_barrier
	s_waitcnt lgkmcnt(0)
	v_mfma_f32_16x16x32_bf16 v[124:127], v[128:131], v[144:147], v[124:127]
	v_mfma_f32_16x16x32_bf16 v[120:123], v[136:139], v[144:147], v[120:123]
	v_mfma_f32_16x16x32_bf16 v[108:111], v[128:131], v[176:179], v[108:111]
	v_mfma_f32_16x16x32_bf16 v[104:107], v[136:139], v[176:179], v[104:107]
	v_mfma_f32_16x16x32_bf16 v[92:95], v[128:131], v[216:219], v[92:95]
	v_mfma_f32_16x16x32_bf16 v[88:91], v[136:139], v[216:219], v[88:91]
	v_mfma_f32_16x16x32_bf16 v[76:79], v[128:131], v[224:227], v[76:79]
	v_mfma_f32_16x16x32_bf16 v[72:75], v[136:139], v[224:227], v[72:75]
	v_mfma_f32_16x16x32_bf16 v[124:127], v[132:135], v[172:175], v[124:127]
	v_mfma_f32_16x16x32_bf16 v[120:123], v[140:143], v[172:175], v[120:123]
	v_mfma_f32_16x16x32_bf16 v[108:111], v[132:135], v[212:215], v[108:111]
	v_mfma_f32_16x16x32_bf16 v[104:107], v[140:143], v[212:215], v[104:107]
	v_mfma_f32_16x16x32_bf16 v[92:95], v[132:135], v[220:223], v[92:95]
	v_mfma_f32_16x16x32_bf16 v[88:91], v[140:143], v[220:223], v[88:91]
	v_mfma_f32_16x16x32_bf16 v[76:79], v[132:135], v[228:231], v[76:79]
	v_mfma_f32_16x16x32_bf16 v[72:75], v[140:143], v[228:231], v[72:75]
	s_barrier
	s_add_i32 s34, 0, 0x1c000
	v_add_u32_e32 v156, s34, v180
	s_add_u32 s34, s10, 0x80
	s_addc_u32 s35, s11, 0
	s_add_i32 m0, s40, 0x18000
	ds_read_b128 v[232:235], v156
	ds_read_b128 v[236:239], v156 offset:1024
	global_load_lds_dwordx4 v150, s[34:35]
	s_add_i32 m0, s40, 0x1a000
	ds_read_b128 v[240:243], v156 offset:2048
	ds_read_b128 v[244:247], v156 offset:3072
	global_load_lds_dwordx4 v154, s[34:35]
	s_barrier
	s_waitcnt lgkmcnt(0)
	v_mfma_f32_16x16x32_bf16 v[116:119], v[232:235], v[144:147], v[116:119]
	v_mfma_f32_16x16x32_bf16 v[112:115], v[240:243], v[144:147], v[112:115]
	v_mfma_f32_16x16x32_bf16 v[100:103], v[232:235], v[176:179], v[100:103]
	v_mfma_f32_16x16x32_bf16 v[96:99], v[240:243], v[176:179], v[96:99]
	v_mfma_f32_16x16x32_bf16 v[84:87], v[232:235], v[216:219], v[84:87]
	v_mfma_f32_16x16x32_bf16 v[80:83], v[240:243], v[216:219], v[80:83]
	v_mfma_f32_16x16x32_bf16 v[68:71], v[232:235], v[224:227], v[68:71]
	v_mfma_f32_16x16x32_bf16 v[64:67], v[240:243], v[224:227], v[64:67]
	v_mfma_f32_16x16x32_bf16 v[116:119], v[236:239], v[172:175], v[116:119]
	v_mfma_f32_16x16x32_bf16 v[112:115], v[244:247], v[172:175], v[112:115]
	v_mfma_f32_16x16x32_bf16 v[100:103], v[236:239], v[212:215], v[100:103]
	v_mfma_f32_16x16x32_bf16 v[96:99], v[244:247], v[212:215], v[96:99]
	v_mfma_f32_16x16x32_bf16 v[84:87], v[236:239], v[220:223], v[84:87]
	v_mfma_f32_16x16x32_bf16 v[80:83], v[244:247], v[220:223], v[80:83]
	v_mfma_f32_16x16x32_bf16 v[68:71], v[236:239], v[228:231], v[68:71]
	v_mfma_f32_16x16x32_bf16 v[64:67], v[244:247], v[228:231], v[64:67]
	s_barrier
	s_add_u32 s34, s72, 0x80
	s_addc_u32 s35, s73, 0
	s_mov_b32 m0, s87
	ds_read_b128 v[144:147], v208 offset:49152
	ds_read_b128 v[172:175], v208 offset:50176
	ds_read_b128 v[176:179], v208 offset:51200
	ds_read_b128 v[212:215], v208 offset:52224
	global_load_lds_dwordx4 v148, s[34:35]
	s_mov_b32 m0, s88
	ds_read_b128 v[216:219], v208 offset:53248
	ds_read_b128 v[220:223], v208 offset:54272
	ds_read_b128 v[224:227], v208 offset:55296
	ds_read_b128 v[228:231], v208 offset:56320
	global_load_lds_dwordx4 v152, s[34:35]
	s_barrier
	s_waitcnt lgkmcnt(0)
	v_mfma_f32_16x16x32_bf16 v[60:63], v[128:131], v[144:147], v[60:63]
	v_mfma_f32_16x16x32_bf16 v[56:59], v[136:139], v[144:147], v[56:59]
	v_mfma_f32_16x16x32_bf16 v[44:47], v[128:131], v[176:179], v[44:47]
	v_mfma_f32_16x16x32_bf16 v[40:43], v[136:139], v[176:179], v[40:43]
	v_mfma_f32_16x16x32_bf16 v[28:31], v[128:131], v[216:219], v[28:31]
	v_mfma_f32_16x16x32_bf16 v[24:27], v[136:139], v[216:219], v[24:27]
	v_mfma_f32_16x16x32_bf16 v[12:15], v[128:131], v[224:227], v[12:15]
	v_mfma_f32_16x16x32_bf16 v[8:11], v[136:139], v[224:227], v[8:11]
	v_mfma_f32_16x16x32_bf16 v[60:63], v[132:135], v[172:175], v[60:63]
	v_mfma_f32_16x16x32_bf16 v[56:59], v[140:143], v[172:175], v[56:59]
	v_mfma_f32_16x16x32_bf16 v[44:47], v[132:135], v[212:215], v[44:47]
	v_mfma_f32_16x16x32_bf16 v[40:43], v[140:143], v[212:215], v[40:43]
	v_mfma_f32_16x16x32_bf16 v[28:31], v[132:135], v[220:223], v[28:31]
	v_mfma_f32_16x16x32_bf16 v[24:27], v[140:143], v[220:223], v[24:27]
	v_mfma_f32_16x16x32_bf16 v[12:15], v[132:135], v[228:231], v[12:15]
	v_mfma_f32_16x16x32_bf16 v[8:11], v[140:143], v[228:231], v[8:11]
	s_barrier
	s_add_u32 s34, s10, 0x80080
	s_addc_u32 s35, s11, 0
	s_add_i32 m0, s40, 0x1c000
	s_add_i32 s74, s74, 2
	global_load_lds_dwordx4 v150, s[34:35]
	s_add_i32 m0, s40, 0x1e000
	s_nop 0
	global_load_lds_dwordx4 v154, s[34:35]
	s_add_u32 s8, s8, 0x100
	s_addc_u32 s9, s9, 0
	s_add_u32 s65, s65, 0x100
	s_addc_u32 s71, s71, 0
	s_waitcnt vmcnt(6)
	s_barrier
	v_mfma_f32_16x16x32_bf16 v[52:55], v[232:235], v[144:147], v[52:55]
	v_mfma_f32_16x16x32_bf16 v[48:51], v[240:243], v[144:147], v[48:51]
	v_mfma_f32_16x16x32_bf16 v[36:39], v[232:235], v[176:179], v[36:39]
	v_mfma_f32_16x16x32_bf16 v[32:35], v[240:243], v[176:179], v[32:35]
	v_add_u32_e32 v140, s91, v180
	v_mfma_f32_16x16x32_bf16 v[20:23], v[232:235], v[216:219], v[20:23]
	v_mfma_f32_16x16x32_bf16 v[16:19], v[240:243], v[216:219], v[16:19]
	ds_read_b128 v[128:131], v140
	v_mfma_f32_16x16x32_bf16 v[4:7], v[232:235], v[224:227], v[4:7]
	v_mfma_f32_16x16x32_bf16 v[0:3], v[240:243], v[224:227], v[0:3]
	ds_read_b128 v[132:135], v140 offset:1024
	v_mfma_f32_16x16x32_bf16 v[52:55], v[236:239], v[172:175], v[52:55]
	v_mfma_f32_16x16x32_bf16 v[48:51], v[244:247], v[172:175], v[48:51]
	ds_read_b128 v[136:139], v140 offset:2048
	v_mfma_f32_16x16x32_bf16 v[36:39], v[236:239], v[212:215], v[36:39]
	v_mfma_f32_16x16x32_bf16 v[32:35], v[244:247], v[212:215], v[32:35]
	ds_read_b128 v[140:143], v140 offset:3072
	v_mfma_f32_16x16x32_bf16 v[20:23], v[236:239], v[220:223], v[20:23]
	v_mfma_f32_16x16x32_bf16 v[16:19], v[244:247], v[220:223], v[16:19]
	v_mfma_f32_16x16x32_bf16 v[4:7], v[236:239], v[228:231], v[4:7]
	v_mfma_f32_16x16x32_bf16 v[0:3], v[244:247], v[228:231], v[0:3]
	s_cmp_gt_u32 s74, 29
	s_barrier
	s_cbranch_scc0 .LBB0_157
	s_waitcnt lgkmcnt(0)
	s_cmp_gt_i32 s70, 15
	s_cselect_b64 s[74:75], -1, 0
	s_cmp_lt_i32 s70, 16
	s_cselect_b64 s[72:73], -1, 0
	s_cmp_gt_i32 s12, 9
	s_mov_b64 s[8:9], -1
	s_cbranch_scc0 .LBB0_338
	s_cmp_gt_u32 s12, 11
	s_cbranch_scc0 .LBB0_272
	s_cmp_gt_u32 s12, 19
	s_mov_b64 s[80:81], -1
	s_cbranch_scc0 .LBB0_173
	s_cmp_gt_u32 s12, 27
	s_cbranch_scc0 .LBB0_170
	s_lshl_b32 s2, s12, 8
	s_cmp_gt_u32 s12, 35
	s_mov_b64 s[8:9], -1
	s_mov_b64 s[78:79], -1
	s_cbranch_scc0 .LBB0_168
	s_cmp_gt_u32 s12, 43
	s_mov_b64 s[10:11], -1
	s_cbranch_scc0 .LBB0_165
	s_add_i32 s20, s2, 0xffffd400
	s_mov_b64 s[10:11], 0

.LBB0_1064:
	s_ashr_i32 s15, s14, 31
	s_lshl_b64 s[20:21], s[14:15], 20
	s_add_u32 s20, s3, s20
	s_addc_u32 s21, s33, s21
	s_and_b64 s[22:23], s[30:31], exec
	s_cselect_b32 s15, s21, s27
	s_cselect_b32 s25, s20, s26
	s_ashr_i32 s17, s16, 31
	s_lshl_b64 s[22:23], s[16:17], 20
	s_add_u32 s22, s38, s22
	s_addc_u32 s23, s39, s23
	s_and_b64 s[30:31], s[30:31], exec
	s_cselect_b32 s17, s23, s29
	s_cselect_b32 s56, s22, s28
	s_add_u32 s26, s26, 0x80080
	s_addc_u32 s27, s27, 0
	s_add_u32 s57, s28, 0x100
	v_mov_b32_e32 v0, 0
	s_addc_u32 s58, s29, 0
	s_mov_b32 s59, -2
	v_mov_b32_e32 v1, v0
	v_mov_b32_e32 v2, v0
	v_mov_b32_e32 v3, v0
	v_mov_b32_e32 v4, v0
	v_mov_b32_e32 v5, v0
	v_mov_b32_e32 v6, v0
	v_mov_b32_e32 v7, v0
	v_mov_b32_e32 v16, v0
	v_mov_b32_e32 v17, v0
	v_mov_b32_e32 v18, v0
	v_mov_b32_e32 v19, v0
	v_mov_b32_e32 v20, v0
	v_mov_b32_e32 v21, v0
	v_mov_b32_e32 v22, v0
	v_mov_b32_e32 v23, v0
	v_mov_b32_e32 v32, v0
	v_mov_b32_e32 v33, v0
	v_mov_b32_e32 v34, v0
	v_mov_b32_e32 v35, v0
	v_mov_b32_e32 v36, v0
	v_mov_b32_e32 v37, v0
	v_mov_b32_e32 v38, v0
	v_mov_b32_e32 v39, v0
	v_mov_b32_e32 v48, v0
	v_mov_b32_e32 v49, v0
	v_mov_b32_e32 v50, v0
	v_mov_b32_e32 v51, v0
	v_mov_b32_e32 v52, v0
	v_mov_b32_e32 v53, v0
	v_mov_b32_e32 v54, v0
	v_mov_b32_e32 v55, v0
	v_mov_b32_e32 v8, v0
	v_mov_b32_e32 v9, v0
	v_mov_b32_e32 v10, v0
	v_mov_b32_e32 v11, v0
	v_mov_b32_e32 v12, v0
	v_mov_b32_e32 v13, v0
	v_mov_b32_e32 v14, v0
	v_mov_b32_e32 v15, v0
	v_mov_b32_e32 v24, v0
	v_mov_b32_e32 v25, v0
	v_mov_b32_e32 v26, v0
	v_mov_b32_e32 v27, v0
	v_mov_b32_e32 v28, v0
	v_mov_b32_e32 v29, v0
	v_mov_b32_e32 v30, v0
	v_mov_b32_e32 v31, v0
	v_mov_b32_e32 v40, v0
	v_mov_b32_e32 v41, v0
	v_mov_b32_e32 v42, v0
	v_mov_b32_e32 v43, v0
	v_mov_b32_e32 v44, v0
	v_mov_b32_e32 v45, v0
	v_mov_b32_e32 v46, v0
	v_mov_b32_e32 v47, v0
	v_mov_b32_e32 v56, v0
	v_mov_b32_e32 v57, v0
	v_mov_b32_e32 v58, v0
	v_mov_b32_e32 v59, v0
	v_mov_b32_e32 v60, v0
	v_mov_b32_e32 v61, v0
	v_mov_b32_e32 v62, v0
	v_mov_b32_e32 v63, v0
	v_mov_b32_e32 v64, v0
	v_mov_b32_e32 v65, v0
	v_mov_b32_e32 v66, v0
	v_mov_b32_e32 v67, v0
	v_mov_b32_e32 v68, v0
	v_mov_b32_e32 v69, v0
	v_mov_b32_e32 v70, v0
	v_mov_b32_e32 v71, v0
	v_mov_b32_e32 v80, v0
	v_mov_b32_e32 v81, v0
	v_mov_b32_e32 v82, v0
	v_mov_b32_e32 v83, v0
	v_mov_b32_e32 v84, v0
	v_mov_b32_e32 v85, v0
	v_mov_b32_e32 v86, v0
	v_mov_b32_e32 v87, v0
	v_mov_b32_e32 v96, v0
	v_mov_b32_e32 v97, v0
	v_mov_b32_e32 v98, v0
	v_mov_b32_e32 v99, v0
	v_mov_b32_e32 v100, v0
	v_mov_b32_e32 v101, v0
	v_mov_b32_e32 v102, v0
	v_mov_b32_e32 v103, v0
	v_mov_b32_e32 v112, v0
	v_mov_b32_e32 v113, v0
	v_mov_b32_e32 v114, v0
	v_mov_b32_e32 v115, v0
	v_mov_b32_e32 v116, v0
	v_mov_b32_e32 v117, v0
	v_mov_b32_e32 v118, v0
	v_mov_b32_e32 v119, v0
	v_mov_b32_e32 v72, v0
	v_mov_b32_e32 v73, v0
	v_mov_b32_e32 v74, v0
	v_mov_b32_e32 v75, v0
	v_mov_b32_e32 v76, v0
	v_mov_b32_e32 v77, v0
	v_mov_b32_e32 v78, v0
	v_mov_b32_e32 v79, v0
	v_mov_b32_e32 v88, v0
	v_mov_b32_e32 v89, v0
	v_mov_b32_e32 v90, v0
	v_mov_b32_e32 v91, v0
	v_mov_b32_e32 v92, v0
	v_mov_b32_e32 v93, v0
	v_mov_b32_e32 v94, v0
	v_mov_b32_e32 v95, v0
	v_mov_b32_e32 v104, v0
	v_mov_b32_e32 v105, v0
	v_mov_b32_e32 v106, v0
	v_mov_b32_e32 v107, v0
	v_mov_b32_e32 v108, v0
	v_mov_b32_e32 v109, v0
	v_mov_b32_e32 v110, v0
	v_mov_b32_e32 v111, v0
	v_mov_b32_e32 v120, v0
	v_mov_b32_e32 v121, v0
	v_mov_b32_e32 v122, v0
	v_mov_b32_e32 v123, v0
	v_mov_b32_e32 v124, v0
	v_mov_b32_e32 v125, v0
	v_mov_b32_e32 v126, v0
	v_mov_b32_e32 v127, v0
	ds_read_b128 v[152:155], v148
	ds_read_b128 v[156:159], v148 offset:1024
	ds_read_b128 v[160:163], v148 offset:2048
	ds_read_b128 v[164:167], v148 offset:3072
	.p2align 7
.LBB0_1065:
	s_add_u32 s28, s26, 0xfff80080
	s_addc_u32 s29, s27, -1
	s_cmp_eq_u32 s59, 28
	s_cselect_b32 s31, s15, s29
	s_cselect_b32 s30, s25, s28
	s_cselect_b32 s29, s17, s58
	s_cselect_b32 s28, s56, s57
	s_add_i32 m0, s47, 0xc000
	ds_read_b128 v[168:171], v149
	ds_read_b128 v[172:175], v149 offset:1024
	ds_read_b128 v[176:179], v149 offset:2048
	ds_read_b128 v[180:183], v149 offset:3072
	global_load_lds_dwordx4 v138, s[26:27]
	s_add_i32 m0, s47, 0xe000
	ds_read_b128 v[186:189], v149 offset:4096
	ds_read_b128 v[190:193], v149 offset:5120
	ds_read_b128 v[194:197], v149 offset:6144
	ds_read_b128 v[198:201], v149 offset:7168
	global_load_lds_dwordx4 v140, s[26:27]
	s_waitcnt lgkmcnt(8)
	s_barrier
	s_waitcnt lgkmcnt(0)
	v_mfma_f32_16x16x32_bf16 v[124:127], v[152:155], v[168:171], v[124:127]
	v_mfma_f32_16x16x32_bf16 v[120:123], v[160:163], v[168:171], v[120:123]
	v_mfma_f32_16x16x32_bf16 v[108:111], v[152:155], v[176:179], v[108:111]
	v_mfma_f32_16x16x32_bf16 v[104:107], v[160:163], v[176:179], v[104:107]
	v_mfma_f32_16x16x32_bf16 v[92:95], v[152:155], v[186:189], v[92:95]
	v_mfma_f32_16x16x32_bf16 v[88:91], v[160:163], v[186:189], v[88:91]
	v_mfma_f32_16x16x32_bf16 v[76:79], v[152:155], v[194:197], v[76:79]
	v_mfma_f32_16x16x32_bf16 v[72:75], v[160:163], v[194:197], v[72:75]
	v_mfma_f32_16x16x32_bf16 v[124:127], v[156:159], v[172:175], v[124:127]
	v_mfma_f32_16x16x32_bf16 v[120:123], v[164:167], v[172:175], v[120:123]
	v_mfma_f32_16x16x32_bf16 v[108:111], v[156:159], v[180:183], v[108:111]
	v_mfma_f32_16x16x32_bf16 v[104:107], v[164:167], v[180:183], v[104:107]
	v_mfma_f32_16x16x32_bf16 v[92:95], v[156:159], v[190:193], v[92:95]
	v_mfma_f32_16x16x32_bf16 v[88:91], v[164:167], v[190:193], v[88:91]
	v_mfma_f32_16x16x32_bf16 v[76:79], v[156:159], v[198:201], v[76:79]
	v_mfma_f32_16x16x32_bf16 v[72:75], v[164:167], v[198:201], v[72:75]
	s_barrier
	s_add_i32 m0, s47, 0x10000
	ds_read_b128 v[202:205], v150
	ds_read_b128 v[206:209], v150 offset:1024
	global_load_lds_dwordx4 v132, s[28:29]
	s_add_i32 m0, s47, 0x12000
	ds_read_b128 v[210:213], v150 offset:2048
	ds_read_b128 v[214:217], v150 offset:3072
	global_load_lds_dwordx4 v128, s[28:29]
	s_barrier
	s_waitcnt lgkmcnt(0)
	v_mfma_f32_16x16x32_bf16 v[116:119], v[202:205], v[168:171], v[116:119]
	v_mfma_f32_16x16x32_bf16 v[112:115], v[210:213], v[168:171], v[112:115]
	v_mfma_f32_16x16x32_bf16 v[100:103], v[202:205], v[176:179], v[100:103]
	v_mfma_f32_16x16x32_bf16 v[96:99], v[210:213], v[176:179], v[96:99]
	v_mfma_f32_16x16x32_bf16 v[84:87], v[202:205], v[186:189], v[84:87]
	v_mfma_f32_16x16x32_bf16 v[80:83], v[210:213], v[186:189], v[80:83]
	v_mfma_f32_16x16x32_bf16 v[68:71], v[202:205], v[194:197], v[68:71]
	v_mfma_f32_16x16x32_bf16 v[64:67], v[210:213], v[194:197], v[64:67]
	v_mfma_f32_16x16x32_bf16 v[116:119], v[206:209], v[172:175], v[116:119]
	v_mfma_f32_16x16x32_bf16 v[112:115], v[214:217], v[172:175], v[112:115]
	v_mfma_f32_16x16x32_bf16 v[100:103], v[206:209], v[180:183], v[100:103]
	v_mfma_f32_16x16x32_bf16 v[96:99], v[214:217], v[180:183], v[96:99]
	v_mfma_f32_16x16x32_bf16 v[84:87], v[206:209], v[190:193], v[84:87]
	v_mfma_f32_16x16x32_bf16 v[80:83], v[214:217], v[190:193], v[80:83]
	v_mfma_f32_16x16x32_bf16 v[68:71], v[206:209], v[198:201], v[68:71]
	v_mfma_f32_16x16x32_bf16 v[64:67], v[214:217], v[198:201], v[64:67]
	s_barrier
	s_mov_b32 m0, s47
	ds_read_b128 v[168:171], v149 offset:16384
	ds_read_b128 v[172:175], v149 offset:17408
	ds_read_b128 v[176:179], v149 offset:18432
	ds_read_b128 v[180:183], v149 offset:19456
	global_load_lds_dwordx4 v134, s[30:31]
	s_mov_b32 m0, s48
	ds_read_b128 v[186:189], v149 offset:20480
	ds_read_b128 v[190:193], v149 offset:21504
	ds_read_b128 v[194:197], v149 offset:22528
	ds_read_b128 v[198:201], v149 offset:23552
	global_load_lds_dwordx4 v130, s[30:31]
	s_barrier
	s_waitcnt lgkmcnt(0)
	v_mfma_f32_16x16x32_bf16 v[60:63], v[152:155], v[168:171], v[60:63]
	v_mfma_f32_16x16x32_bf16 v[56:59], v[160:163], v[168:171], v[56:59]
	v_mfma_f32_16x16x32_bf16 v[44:47], v[152:155], v[176:179], v[44:47]
	v_mfma_f32_16x16x32_bf16 v[40:43], v[160:163], v[176:179], v[40:43]
	v_mfma_f32_16x16x32_bf16 v[28:31], v[152:155], v[186:189], v[28:31]
	v_mfma_f32_16x16x32_bf16 v[24:27], v[160:163], v[186:189], v[24:27]
	v_mfma_f32_16x16x32_bf16 v[12:15], v[152:155], v[194:197], v[12:15]
	v_mfma_f32_16x16x32_bf16 v[8:11], v[160:163], v[194:197], v[8:11]
	v_mfma_f32_16x16x32_bf16 v[60:63], v[156:159], v[172:175], v[60:63]
	v_mfma_f32_16x16x32_bf16 v[56:59], v[164:167], v[172:175], v[56:59]
	v_mfma_f32_16x16x32_bf16 v[44:47], v[156:159], v[180:183], v[44:47]
	v_mfma_f32_16x16x32_bf16 v[40:43], v[164:167], v[180:183], v[40:43]
	v_mfma_f32_16x16x32_bf16 v[28:31], v[156:159], v[190:193], v[28:31]
	v_mfma_f32_16x16x32_bf16 v[24:27], v[164:167], v[190:193], v[24:27]
	v_mfma_f32_16x16x32_bf16 v[12:15], v[156:159], v[198:201], v[12:15]
	v_mfma_f32_16x16x32_bf16 v[8:11], v[164:167], v[198:201], v[8:11]
	s_barrier
	s_add_u32 s34, s28, 0x80000
	s_addc_u32 s35, s29, 0
	s_add_i32 m0, s47, 0x14000
	s_nop 0
	global_load_lds_dwordx4 v132, s[34:35]
	s_add_i32 m0, s47, 0x16000
	s_nop 0
	global_load_lds_dwordx4 v128, s[34:35]
	s_waitcnt vmcnt(6)
	s_barrier
	v_mfma_f32_16x16x32_bf16 v[52:55], v[202:205], v[168:171], v[52:55]
	v_mfma_f32_16x16x32_bf16 v[48:51], v[210:213], v[168:171], v[48:51]
	v_mfma_f32_16x16x32_bf16 v[36:39], v[202:205], v[176:179], v[36:39]
	v_mfma_f32_16x16x32_bf16 v[32:35], v[210:213], v[176:179], v[32:35]
	s_add_i32 s34, 0, 0x18000
	v_mfma_f32_16x16x32_bf16 v[20:23], v[202:205], v[186:189], v[20:23]
	v_mfma_f32_16x16x32_bf16 v[16:19], v[210:213], v[186:189], v[16:19]
	v_add_u32_e32 v151, s34, v147
	v_mfma_f32_16x16x32_bf16 v[4:7], v[202:205], v[194:197], v[4:7]
	v_mfma_f32_16x16x32_bf16 v[0:3], v[210:213], v[194:197], v[0:3]
	ds_read_b128 v[152:155], v151
	v_mfma_f32_16x16x32_bf16 v[52:55], v[206:209], v[172:175], v[52:55]
	v_mfma_f32_16x16x32_bf16 v[48:51], v[214:217], v[172:175], v[48:51]
	ds_read_b128 v[156:159], v151 offset:1024
	v_mfma_f32_16x16x32_bf16 v[36:39], v[206:209], v[180:183], v[36:39]
	v_mfma_f32_16x16x32_bf16 v[32:35], v[214:217], v[180:183], v[32:35]
	ds_read_b128 v[160:163], v151 offset:2048
	v_mfma_f32_16x16x32_bf16 v[20:23], v[206:209], v[190:193], v[20:23]
	v_mfma_f32_16x16x32_bf16 v[16:19], v[214:217], v[190:193], v[16:19]
	ds_read_b128 v[164:167], v151 offset:3072
	v_mfma_f32_16x16x32_bf16 v[4:7], v[206:209], v[198:201], v[4:7]
	v_mfma_f32_16x16x32_bf16 v[0:3], v[214:217], v[198:201], v[0:3]
	s_barrier
	s_add_u32 s34, s30, 0x80000
	s_addc_u32 s35, s31, 0
	s_mov_b32 m0, s49
	ds_read_b128 v[168:171], v149 offset:32768
	ds_read_b128 v[172:175], v149 offset:33792
	ds_read_b128 v[176:179], v149 offset:34816
	ds_read_b128 v[180:183], v149 offset:35840
	global_load_lds_dwordx4 v134, s[34:35]
	s_mov_b32 m0, s50
	ds_read_b128 v[186:189], v149 offset:36864
	ds_read_b128 v[190:193], v149 offset:37888
	ds_read_b128 v[194:197], v149 offset:38912
	ds_read_b128 v[198:201], v149 offset:39936
	global_load_lds_dwordx4 v130, s[34:35]
	s_waitcnt lgkmcnt(8)
	s_barrier
	s_waitcnt lgkmcnt(0)
	v_mfma_f32_16x16x32_bf16 v[124:127], v[152:155], v[168:171], v[124:127]
	v_mfma_f32_16x16x32_bf16 v[120:123], v[160:163], v[168:171], v[120:123]
	v_mfma_f32_16x16x32_bf16 v[108:111], v[152:155], v[176:179], v[108:111]
	v_mfma_f32_16x16x32_bf16 v[104:107], v[160:163], v[176:179], v[104:107]
	v_mfma_f32_16x16x32_bf16 v[92:95], v[152:155], v[186:189], v[92:95]
	v_mfma_f32_16x16x32_bf16 v[88:91], v[160:163], v[186:189], v[88:91]
	v_mfma_f32_16x16x32_bf16 v[76:79], v[152:155], v[194:197], v[76:79]
	v_mfma_f32_16x16x32_bf16 v[72:75], v[160:163], v[194:197], v[72:75]
	v_mfma_f32_16x16x32_bf16 v[124:127], v[156:159], v[172:175], v[124:127]
	v_mfma_f32_16x16x32_bf16 v[120:123], v[164:167], v[172:175], v[120:123]
	v_mfma_f32_16x16x32_bf16 v[108:111], v[156:159], v[180:183], v[108:111]
	v_mfma_f32_16x16x32_bf16 v[104:107], v[164:167], v[180:183], v[104:107]
	v_mfma_f32_16x16x32_bf16 v[92:95], v[156:159], v[190:193], v[92:95]
	v_mfma_f32_16x16x32_bf16 v[88:91], v[164:167], v[190:193], v[88:91]
	v_mfma_f32_16x16x32_bf16 v[76:79], v[156:159], v[198:201], v[76:79]
	v_mfma_f32_16x16x32_bf16 v[72:75], v[164:167], v[198:201], v[72:75]
	s_barrier
	s_add_i32 s34, 0, 0x1c000
	v_add_u32_e32 v151, s34, v147
	s_add_u32 s34, s28, 0x80
	s_addc_u32 s35, s29, 0
	s_add_i32 m0, s47, 0x18000
	ds_read_b128 v[202:205], v151
	ds_read_b128 v[206:209], v151 offset:1024
	global_load_lds_dwordx4 v132, s[34:35]
	s_add_i32 m0, s47, 0x1a000
	ds_read_b128 v[210:213], v151 offset:2048
	ds_read_b128 v[214:217], v151 offset:3072
	global_load_lds_dwordx4 v128, s[34:35]
	s_barrier
	s_waitcnt lgkmcnt(0)
	v_mfma_f32_16x16x32_bf16 v[116:119], v[202:205], v[168:171], v[116:119]
	v_mfma_f32_16x16x32_bf16 v[112:115], v[210:213], v[168:171], v[112:115]
	v_mfma_f32_16x16x32_bf16 v[100:103], v[202:205], v[176:179], v[100:103]
	v_mfma_f32_16x16x32_bf16 v[96:99], v[210:213], v[176:179], v[96:99]
	v_mfma_f32_16x16x32_bf16 v[84:87], v[202:205], v[186:189], v[84:87]
	v_mfma_f32_16x16x32_bf16 v[80:83], v[210:213], v[186:189], v[80:83]
	v_mfma_f32_16x16x32_bf16 v[68:71], v[202:205], v[194:197], v[68:71]
	v_mfma_f32_16x16x32_bf16 v[64:67], v[210:213], v[194:197], v[64:67]
	v_mfma_f32_16x16x32_bf16 v[116:119], v[206:209], v[172:175], v[116:119]
	v_mfma_f32_16x16x32_bf16 v[112:115], v[214:217], v[172:175], v[112:115]
	v_mfma_f32_16x16x32_bf16 v[100:103], v[206:209], v[180:183], v[100:103]
	v_mfma_f32_16x16x32_bf16 v[96:99], v[214:217], v[180:183], v[96:99]
	v_mfma_f32_16x16x32_bf16 v[84:87], v[206:209], v[190:193], v[84:87]
	v_mfma_f32_16x16x32_bf16 v[80:83], v[214:217], v[190:193], v[80:83]
	v_mfma_f32_16x16x32_bf16 v[68:71], v[206:209], v[198:201], v[68:71]
	v_mfma_f32_16x16x32_bf16 v[64:67], v[214:217], v[198:201], v[64:67]
	s_barrier
	s_add_u32 s34, s30, 0x80
	s_addc_u32 s35, s31, 0
	s_mov_b32 m0, s51
	ds_read_b128 v[168:171], v149 offset:49152
	ds_read_b128 v[172:175], v149 offset:50176
	ds_read_b128 v[176:179], v149 offset:51200
	ds_read_b128 v[180:183], v149 offset:52224
	global_load_lds_dwordx4 v134, s[34:35]
	s_mov_b32 m0, s52
	ds_read_b128 v[186:189], v149 offset:53248
	ds_read_b128 v[190:193], v149 offset:54272
	ds_read_b128 v[194:197], v149 offset:55296
	ds_read_b128 v[198:201], v149 offset:56320
	global_load_lds_dwordx4 v130, s[34:35]
	s_barrier
	s_waitcnt lgkmcnt(0)
	v_mfma_f32_16x16x32_bf16 v[60:63], v[152:155], v[168:171], v[60:63]
	v_mfma_f32_16x16x32_bf16 v[56:59], v[160:163], v[168:171], v[56:59]
	v_mfma_f32_16x16x32_bf16 v[44:47], v[152:155], v[176:179], v[44:47]
	v_mfma_f32_16x16x32_bf16 v[40:43], v[160:163], v[176:179], v[40:43]
	v_mfma_f32_16x16x32_bf16 v[28:31], v[152:155], v[186:189], v[28:31]
	v_mfma_f32_16x16x32_bf16 v[24:27], v[160:163], v[186:189], v[24:27]
	v_mfma_f32_16x16x32_bf16 v[12:15], v[152:155], v[194:197], v[12:15]
	v_mfma_f32_16x16x32_bf16 v[8:11], v[160:163], v[194:197], v[8:11]
	v_mfma_f32_16x16x32_bf16 v[60:63], v[156:159], v[172:175], v[60:63]
	v_mfma_f32_16x16x32_bf16 v[56:59], v[164:167], v[172:175], v[56:59]
	v_mfma_f32_16x16x32_bf16 v[44:47], v[156:159], v[180:183], v[44:47]
	v_mfma_f32_16x16x32_bf16 v[40:43], v[164:167], v[180:183], v[40:43]
	v_mfma_f32_16x16x32_bf16 v[28:31], v[156:159], v[190:193], v[28:31]
	v_mfma_f32_16x16x32_bf16 v[24:27], v[164:167], v[190:193], v[24:27]
	v_mfma_f32_16x16x32_bf16 v[12:15], v[156:159], v[198:201], v[12:15]
	v_mfma_f32_16x16x32_bf16 v[8:11], v[164:167], v[198:201], v[8:11]
	s_barrier
	s_add_u32 s34, s28, 0x80080
	s_addc_u32 s35, s29, 0
	s_add_i32 m0, s47, 0x1c000
	s_add_i32 s59, s59, 2
	global_load_lds_dwordx4 v132, s[34:35]
	s_add_i32 m0, s47, 0x1e000
	s_nop 0
	global_load_lds_dwordx4 v128, s[34:35]
	s_add_u32 s26, s26, 0x100
	s_addc_u32 s27, s27, 0
	s_add_u32 s57, s57, 0x100
	s_addc_u32 s58, s58, 0
	s_waitcnt vmcnt(6)
	s_barrier
	v_mfma_f32_16x16x32_bf16 v[52:55], v[202:205], v[168:171], v[52:55]
	v_mfma_f32_16x16x32_bf16 v[48:51], v[210:213], v[168:171], v[48:51]
	v_mfma_f32_16x16x32_bf16 v[36:39], v[202:205], v[176:179], v[36:39]
	v_mfma_f32_16x16x32_bf16 v[32:35], v[210:213], v[176:179], v[32:35]
	ds_read_b128 v[152:155], v148
	v_mfma_f32_16x16x32_bf16 v[20:23], v[202:205], v[186:189], v[20:23]
	v_mfma_f32_16x16x32_bf16 v[16:19], v[210:213], v[186:189], v[16:19]
	ds_read_b128 v[156:159], v148 offset:1024
	v_mfma_f32_16x16x32_bf16 v[4:7], v[202:205], v[194:197], v[4:7]
	v_mfma_f32_16x16x32_bf16 v[0:3], v[210:213], v[194:197], v[0:3]
	ds_read_b128 v[160:163], v148 offset:2048
	v_mfma_f32_16x16x32_bf16 v[52:55], v[206:209], v[172:175], v[52:55]
	v_mfma_f32_16x16x32_bf16 v[48:51], v[214:217], v[172:175], v[48:51]
	ds_read_b128 v[164:167], v148 offset:3072
	v_mfma_f32_16x16x32_bf16 v[36:39], v[206:209], v[180:183], v[36:39]
	v_mfma_f32_16x16x32_bf16 v[32:35], v[214:217], v[180:183], v[32:35]
	v_mfma_f32_16x16x32_bf16 v[20:23], v[206:209], v[190:193], v[20:23]
	v_mfma_f32_16x16x32_bf16 v[16:19], v[214:217], v[190:193], v[16:19]
	v_mfma_f32_16x16x32_bf16 v[4:7], v[206:209], v[198:201], v[4:7]
	v_mfma_f32_16x16x32_bf16 v[0:3], v[214:217], v[198:201], v[0:3]
	s_cmp_gt_u32 s59, 29
	s_barrier
	s_cbranch_scc0 .LBB0_1065
	s_waitcnt lgkmcnt(0)
	v_mul_f32_e32 v154, 0xbfb8aa3b, v124
	v_exp_f32_e32 v154, v154
	v_mul_f32_e32 v155, 0xbfb8aa3b, v125
	v_exp_f32_e32 v155, v155
	v_lshl_add_u32 v151, s24, 8, v146
	v_add_f32_e32 v154, 1.0, v154
	v_rcp_f32_e32 v154, v154
	v_add_f32_e32 v155, 1.0, v155
	v_rcp_f32_e32 v155, v155
	s_lshl_b32 s24, s13, 7
	v_mul_f32_e32 v124, v124, v154
	v_mul_f32_e32 v120, v120, v124
	v_mul_f32_e32 v124, v125, v155
	v_mul_f32_e32 v125, 0xbfb8aa3b, v126
	v_exp_f32_e32 v125, v125
	v_mul_f32_e32 v154, 0xbfb8aa3b, v127
	v_exp_f32_e32 v154, v154
	v_mul_f32_e32 v121, v121, v124
	v_add_f32_e32 v124, 1.0, v125
	v_rcp_f32_e32 v124, v124
	v_add_f32_e32 v125, 1.0, v154
	v_rcp_f32_e32 v125, v125
	v_cvt_pk_bf16_f32 v120, v120, v121
	v_mul_f32_e32 v121, v126, v124
	v_mul_f32_e32 v121, v122, v121
	v_mul_f32_e32 v122, v127, v125
	v_mul_f32_e32 v122, v123, v122
	v_mul_f32_e32 v123, 0xbfb8aa3b, v116
	v_exp_f32_e32 v123, v123
	v_mul_f32_e32 v124, 0xbfb8aa3b, v117
	v_exp_f32_e32 v124, v124
	v_cvt_pk_bf16_f32 v121, v121, v122
	v_add_f32_e32 v122, 1.0, v123
	v_rcp_f32_e32 v122, v122
	v_add_f32_e32 v123, 1.0, v124
	s_ashr_i32 s25, s24, 31
	v_mov_b64_e32 v[144:145], s[6:7]
	v_rcp_f32_e32 v123, v123
	v_mad_i64_i32 v[152:153], s[26:27], v151, s55, v[144:145]
	s_lshl_b64 s[24:25], s[24:25], 1
	v_lshl_add_u64 v[152:153], v[152:153], 0, s[24:25]
	s_mov_b32 s13, s9
	v_lshl_add_u64 v[152:153], v[152:153], 0, s[12:13]
	v_mul_f32_e32 v116, v116, v122
	v_lshl_add_u64 v[152:153], v[152:153], 0, v[136:137]
	v_mul_f32_e32 v112, v112, v116
	v_mul_f32_e32 v116, v117, v123
	v_mul_f32_e32 v117, 0xbfb8aa3b, v118
	global_store_dwordx2 v[152:153], v[120:121], off
	v_exp_f32_e32 v117, v117
	v_mul_f32_e32 v120, 0xbfb8aa3b, v119
	v_exp_f32_e32 v120, v120
	v_mul_f32_e32 v113, v113, v116
	v_add_f32_e32 v116, 1.0, v117
	v_rcp_f32_e32 v116, v116
	v_add_f32_e32 v117, 1.0, v120
	v_rcp_f32_e32 v117, v117
	v_cvt_pk_bf16_f32 v112, v112, v113
	v_mul_f32_e32 v113, v118, v116
	v_mul_f32_e32 v113, v114, v113
	v_mul_f32_e32 v114, v119, v117
	v_mul_f32_e32 v114, v115, v114
	v_cvt_pk_bf16_f32 v113, v113, v114
	v_mul_f32_e32 v114, 0xbfb8aa3b, v108
	v_exp_f32_e32 v114, v114
	v_mul_f32_e32 v115, 0xbfb8aa3b, v109
	v_exp_f32_e32 v115, v115
	global_store_dwordx2 v[152:153], v[112:113], off offset:128
	v_add_f32_e32 v114, 1.0, v114
	v_rcp_f32_e32 v114, v114
	v_add_f32_e32 v115, 1.0, v115
	v_rcp_f32_e32 v115, v115
	v_or_b32_e32 v112, 16, v151
	v_mul_f32_e32 v108, v108, v114
	v_mul_f32_e32 v104, v104, v108
	v_mul_f32_e32 v108, v109, v115
	v_mul_f32_e32 v109, 0xbfb8aa3b, v110
	v_exp_f32_e32 v109, v109
	v_mul_f32_e32 v114, 0xbfb8aa3b, v111
	v_exp_f32_e32 v114, v114
	v_mul_f32_e32 v105, v105, v108
	v_add_f32_e32 v108, 1.0, v109
	v_rcp_f32_e32 v108, v108
	v_add_f32_e32 v109, 1.0, v114
	v_rcp_f32_e32 v109, v109
	v_cvt_pk_bf16_f32 v104, v104, v105
	v_mul_f32_e32 v105, v110, v108
	v_mul_f32_e32 v105, v106, v105
	v_mul_f32_e32 v106, v111, v109
	v_mul_f32_e32 v106, v107, v106
	v_mul_f32_e32 v107, 0xbfb8aa3b, v100
	v_exp_f32_e32 v107, v107
	v_mul_f32_e32 v108, 0xbfb8aa3b, v101
	v_exp_f32_e32 v108, v108
	v_cvt_pk_bf16_f32 v105, v105, v106
	v_add_f32_e32 v106, 1.0, v107
	v_rcp_f32_e32 v106, v106
	v_add_f32_e32 v107, 1.0, v108
	v_rcp_f32_e32 v107, v107
	v_mad_i64_i32 v[112:113], s[26:27], v112, s55, v[144:145]
	v_lshl_add_u64 v[112:113], v[112:113], 0, s[24:25]
	v_lshl_add_u64 v[112:113], v[112:113], 0, s[12:13]
	v_mul_f32_e32 v100, v100, v106
	v_lshl_add_u64 v[112:113], v[112:113], 0, v[136:137]
	v_mul_f32_e32 v96, v96, v100
	v_mul_f32_e32 v100, v101, v107
	v_mul_f32_e32 v101, 0xbfb8aa3b, v102
	global_store_dwordx2 v[112:113], v[104:105], off
	v_exp_f32_e32 v101, v101
	v_mul_f32_e32 v104, 0xbfb8aa3b, v103
	v_exp_f32_e32 v104, v104
	v_mul_f32_e32 v97, v97, v100
	v_add_f32_e32 v100, 1.0, v101
	v_rcp_f32_e32 v100, v100
	v_add_f32_e32 v101, 1.0, v104
	v_rcp_f32_e32 v101, v101
	v_cvt_pk_bf16_f32 v96, v96, v97
	v_mul_f32_e32 v97, v102, v100
	v_mul_f32_e32 v97, v98, v97
	v_mul_f32_e32 v98, v103, v101
	v_mul_f32_e32 v98, v99, v98
	v_cvt_pk_bf16_f32 v97, v97, v98
	v_mul_f32_e32 v98, 0xbfb8aa3b, v92
	v_exp_f32_e32 v98, v98
	v_mul_f32_e32 v99, 0xbfb8aa3b, v93
	v_exp_f32_e32 v99, v99
	global_store_dwordx2 v[112:113], v[96:97], off offset:128
	v_add_f32_e32 v98, 1.0, v98
	v_rcp_f32_e32 v98, v98
	v_add_f32_e32 v99, 1.0, v99
	v_rcp_f32_e32 v99, v99
	v_or_b32_e32 v96, 32, v151
	v_mul_f32_e32 v92, v92, v98
	v_mul_f32_e32 v88, v88, v92
	v_mul_f32_e32 v92, v93, v99
	v_mul_f32_e32 v93, 0xbfb8aa3b, v94
	v_exp_f32_e32 v93, v93
	v_mul_f32_e32 v98, 0xbfb8aa3b, v95
	v_exp_f32_e32 v98, v98
	v_mul_f32_e32 v89, v89, v92
	v_add_f32_e32 v92, 1.0, v93
	v_rcp_f32_e32 v92, v92
	v_add_f32_e32 v93, 1.0, v98
	v_rcp_f32_e32 v93, v93
	v_cvt_pk_bf16_f32 v88, v88, v89
	v_mul_f32_e32 v89, v94, v92
	v_mul_f32_e32 v89, v90, v89
	v_mul_f32_e32 v90, v95, v93
	v_mul_f32_e32 v90, v91, v90
	v_mul_f32_e32 v91, 0xbfb8aa3b, v84
	v_exp_f32_e32 v91, v91
	v_mul_f32_e32 v92, 0xbfb8aa3b, v85
	v_exp_f32_e32 v92, v92
	v_cvt_pk_bf16_f32 v89, v89, v90
	v_add_f32_e32 v90, 1.0, v91
	v_rcp_f32_e32 v90, v90
	v_add_f32_e32 v91, 1.0, v92
	v_rcp_f32_e32 v91, v91
	v_mad_i64_i32 v[96:97], s[26:27], v96, s55, v[144:145]
	v_lshl_add_u64 v[96:97], v[96:97], 0, s[24:25]
	v_lshl_add_u64 v[96:97], v[96:97], 0, s[12:13]
	v_mul_f32_e32 v84, v84, v90
	v_lshl_add_u64 v[96:97], v[96:97], 0, v[136:137]
	v_mul_f32_e32 v80, v80, v84
	v_mul_f32_e32 v84, v85, v91
	v_mul_f32_e32 v85, 0xbfb8aa3b, v86
	global_store_dwordx2 v[96:97], v[88:89], off
	v_exp_f32_e32 v85, v85
	v_mul_f32_e32 v88, 0xbfb8aa3b, v87
	v_exp_f32_e32 v88, v88
	v_mul_f32_e32 v81, v81, v84
	v_add_f32_e32 v84, 1.0, v85
	v_rcp_f32_e32 v84, v84
	v_add_f32_e32 v85, 1.0, v88
	v_rcp_f32_e32 v85, v85
	v_cvt_pk_bf16_f32 v80, v80, v81
	v_mul_f32_e32 v81, v86, v84
	v_mul_f32_e32 v81, v82, v81
	v_mul_f32_e32 v82, v87, v85
	v_mul_f32_e32 v82, v83, v82
	v_cvt_pk_bf16_f32 v81, v81, v82
	v_mul_f32_e32 v82, 0xbfb8aa3b, v76
	v_exp_f32_e32 v82, v82
	v_mul_f32_e32 v83, 0xbfb8aa3b, v77
	v_exp_f32_e32 v83, v83
	global_store_dwordx2 v[96:97], v[80:81], off offset:128
	v_add_f32_e32 v82, 1.0, v82
	v_rcp_f32_e32 v82, v82
	v_add_f32_e32 v83, 1.0, v83
	v_rcp_f32_e32 v83, v83
	v_or_b32_e32 v80, 48, v151
	v_mul_f32_e32 v76, v76, v82
	v_mul_f32_e32 v72, v72, v76
	v_mul_f32_e32 v76, v77, v83
	v_mul_f32_e32 v77, 0xbfb8aa3b, v78
	v_exp_f32_e32 v77, v77
	v_mul_f32_e32 v82, 0xbfb8aa3b, v79
	v_exp_f32_e32 v82, v82
	v_mul_f32_e32 v73, v73, v76
	v_add_f32_e32 v76, 1.0, v77
	v_rcp_f32_e32 v76, v76
	v_add_f32_e32 v77, 1.0, v82
	v_rcp_f32_e32 v77, v77
	v_cvt_pk_bf16_f32 v72, v72, v73
	v_mul_f32_e32 v73, v78, v76
	v_mul_f32_e32 v73, v74, v73
	v_mul_f32_e32 v74, v79, v77
	v_mul_f32_e32 v74, v75, v74
	v_mul_f32_e32 v75, 0xbfb8aa3b, v68
	v_exp_f32_e32 v75, v75
	v_mul_f32_e32 v76, 0xbfb8aa3b, v69
	v_exp_f32_e32 v76, v76
	v_cvt_pk_bf16_f32 v73, v73, v74
	v_add_f32_e32 v74, 1.0, v75
	v_rcp_f32_e32 v74, v74
	v_add_f32_e32 v75, 1.0, v76
	v_rcp_f32_e32 v75, v75
	v_mad_i64_i32 v[80:81], s[26:27], v80, s55, v[144:145]
	v_lshl_add_u64 v[80:81], v[80:81], 0, s[24:25]
	v_lshl_add_u64 v[80:81], v[80:81], 0, s[12:13]
	v_mul_f32_e32 v68, v68, v74
	v_lshl_add_u64 v[80:81], v[80:81], 0, v[136:137]
	v_mul_f32_e32 v64, v64, v68
	v_mul_f32_e32 v68, v69, v75
	v_mul_f32_e32 v69, 0xbfb8aa3b, v70
	global_store_dwordx2 v[80:81], v[72:73], off
	v_exp_f32_e32 v69, v69
	v_mul_f32_e32 v72, 0xbfb8aa3b, v71
	v_exp_f32_e32 v72, v72
	v_mul_f32_e32 v65, v65, v68
	v_add_f32_e32 v68, 1.0, v69
	v_rcp_f32_e32 v68, v68
	v_add_f32_e32 v69, 1.0, v72
	v_rcp_f32_e32 v69, v69
	v_cvt_pk_bf16_f32 v64, v64, v65
	v_mul_f32_e32 v65, v70, v68
	v_mul_f32_e32 v65, v66, v65
	v_mul_f32_e32 v66, v71, v69
	v_mul_f32_e32 v66, v67, v66
	v_cvt_pk_bf16_f32 v65, v65, v66
	v_mul_f32_e32 v66, 0xbfb8aa3b, v60
	v_exp_f32_e32 v66, v66
	v_mul_f32_e32 v67, 0xbfb8aa3b, v61
	v_exp_f32_e32 v67, v67
	global_store_dwordx2 v[80:81], v[64:65], off offset:128
	v_add_f32_e32 v66, 1.0, v66
	v_rcp_f32_e32 v66, v66
	v_add_f32_e32 v67, 1.0, v67
	v_rcp_f32_e32 v67, v67
	v_add_u32_e32 v64, 0x80, v151
	v_mul_f32_e32 v60, v60, v66
	v_mul_f32_e32 v56, v56, v60
	v_mul_f32_e32 v60, v61, v67
	v_mul_f32_e32 v61, 0xbfb8aa3b, v62
	v_exp_f32_e32 v61, v61
	v_mul_f32_e32 v66, 0xbfb8aa3b, v63
	v_exp_f32_e32 v66, v66
	v_mul_f32_e32 v57, v57, v60
	v_add_f32_e32 v60, 1.0, v61
	v_rcp_f32_e32 v60, v60
	v_add_f32_e32 v61, 1.0, v66
	v_rcp_f32_e32 v61, v61
	v_cvt_pk_bf16_f32 v56, v56, v57
	v_mul_f32_e32 v57, v62, v60
	v_mul_f32_e32 v57, v58, v57
	v_mul_f32_e32 v58, v63, v61
	v_mul_f32_e32 v58, v59, v58
	v_mul_f32_e32 v59, 0xbfb8aa3b, v52
	v_exp_f32_e32 v59, v59
	v_mul_f32_e32 v60, 0xbfb8aa3b, v53
	v_exp_f32_e32 v60, v60
	v_cvt_pk_bf16_f32 v57, v57, v58
	v_add_f32_e32 v58, 1.0, v59
	v_rcp_f32_e32 v58, v58
	v_add_f32_e32 v59, 1.0, v60
	v_rcp_f32_e32 v59, v59
	v_mad_i64_i32 v[64:65], s[26:27], v64, s55, v[144:145]
	v_lshl_add_u64 v[64:65], v[64:65], 0, s[24:25]
	v_lshl_add_u64 v[64:65], v[64:65], 0, s[12:13]
	v_mul_f32_e32 v52, v52, v58
	v_lshl_add_u64 v[64:65], v[64:65], 0, v[136:137]
	v_mul_f32_e32 v48, v48, v52
	v_mul_f32_e32 v52, v53, v59
	v_mul_f32_e32 v53, 0xbfb8aa3b, v54
	global_store_dwordx2 v[64:65], v[56:57], off
	v_exp_f32_e32 v53, v53
	v_mul_f32_e32 v56, 0xbfb8aa3b, v55
	v_exp_f32_e32 v56, v56
	v_mul_f32_e32 v49, v49, v52
	v_add_f32_e32 v52, 1.0, v53
	v_rcp_f32_e32 v52, v52
	v_add_f32_e32 v53, 1.0, v56
	v_rcp_f32_e32 v53, v53
	v_cvt_pk_bf16_f32 v48, v48, v49
	v_mul_f32_e32 v49, v54, v52
	v_mul_f32_e32 v49, v50, v49
	v_mul_f32_e32 v50, v55, v53
	v_mul_f32_e32 v50, v51, v50
	v_cvt_pk_bf16_f32 v49, v49, v50
	v_mul_f32_e32 v50, 0xbfb8aa3b, v44
	v_exp_f32_e32 v50, v50
	v_mul_f32_e32 v51, 0xbfb8aa3b, v45
	v_exp_f32_e32 v51, v51
	global_store_dwordx2 v[64:65], v[48:49], off offset:128
	v_add_f32_e32 v50, 1.0, v50
	v_rcp_f32_e32 v50, v50
	v_add_f32_e32 v51, 1.0, v51
	v_rcp_f32_e32 v51, v51
	v_add_u32_e32 v48, 0x90, v151
	v_mul_f32_e32 v44, v44, v50
	v_mul_f32_e32 v40, v40, v44
	v_mul_f32_e32 v44, v45, v51
	v_mul_f32_e32 v45, 0xbfb8aa3b, v46
	v_exp_f32_e32 v45, v45
	v_mul_f32_e32 v50, 0xbfb8aa3b, v47
	v_exp_f32_e32 v50, v50
	v_mul_f32_e32 v41, v41, v44
	v_add_f32_e32 v44, 1.0, v45
	v_rcp_f32_e32 v44, v44
	v_add_f32_e32 v45, 1.0, v50
	v_rcp_f32_e32 v45, v45
	v_cvt_pk_bf16_f32 v40, v40, v41
	v_mul_f32_e32 v41, v46, v44
	v_mul_f32_e32 v41, v42, v41
	v_mul_f32_e32 v42, v47, v45
	v_mul_f32_e32 v42, v43, v42
	v_mul_f32_e32 v43, 0xbfb8aa3b, v36
	v_exp_f32_e32 v43, v43
	v_mul_f32_e32 v44, 0xbfb8aa3b, v37
	v_exp_f32_e32 v44, v44
	v_cvt_pk_bf16_f32 v41, v41, v42
	v_add_f32_e32 v42, 1.0, v43
	v_rcp_f32_e32 v42, v42
	v_add_f32_e32 v43, 1.0, v44
	v_rcp_f32_e32 v43, v43
	v_mad_i64_i32 v[48:49], s[26:27], v48, s55, v[144:145]
	v_lshl_add_u64 v[48:49], v[48:49], 0, s[24:25]
	v_lshl_add_u64 v[48:49], v[48:49], 0, s[12:13]
	v_mul_f32_e32 v36, v36, v42
	v_lshl_add_u64 v[48:49], v[48:49], 0, v[136:137]
	v_mul_f32_e32 v32, v32, v36
	v_mul_f32_e32 v36, v37, v43
	v_mul_f32_e32 v37, 0xbfb8aa3b, v38
	global_store_dwordx2 v[48:49], v[40:41], off
	v_exp_f32_e32 v37, v37
	v_mul_f32_e32 v40, 0xbfb8aa3b, v39
	v_exp_f32_e32 v40, v40
	v_mul_f32_e32 v33, v33, v36
	v_add_f32_e32 v36, 1.0, v37
	v_rcp_f32_e32 v36, v36
	v_add_f32_e32 v37, 1.0, v40
	v_rcp_f32_e32 v37, v37
	v_cvt_pk_bf16_f32 v32, v32, v33
	v_mul_f32_e32 v33, v38, v36
	v_mul_f32_e32 v33, v34, v33
	v_mul_f32_e32 v34, v39, v37
	v_mul_f32_e32 v34, v35, v34
	v_cvt_pk_bf16_f32 v33, v33, v34
	v_mul_f32_e32 v34, 0xbfb8aa3b, v28
	v_exp_f32_e32 v34, v34
	v_mul_f32_e32 v35, 0xbfb8aa3b, v29
	v_exp_f32_e32 v35, v35
	global_store_dwordx2 v[48:49], v[32:33], off offset:128
	v_add_f32_e32 v34, 1.0, v34
	v_rcp_f32_e32 v34, v34
	v_add_f32_e32 v35, 1.0, v35
	v_rcp_f32_e32 v35, v35
	v_add_u32_e32 v32, 0xa0, v151
	v_mul_f32_e32 v28, v28, v34
	v_mul_f32_e32 v24, v24, v28
	v_mul_f32_e32 v28, v29, v35
	v_mul_f32_e32 v29, 0xbfb8aa3b, v30
	v_exp_f32_e32 v29, v29
	v_mul_f32_e32 v34, 0xbfb8aa3b, v31
	v_exp_f32_e32 v34, v34
	v_mul_f32_e32 v25, v25, v28
	v_add_f32_e32 v28, 1.0, v29
	v_rcp_f32_e32 v28, v28
	v_add_f32_e32 v29, 1.0, v34
	v_rcp_f32_e32 v29, v29
	v_cvt_pk_bf16_f32 v24, v24, v25
	v_mul_f32_e32 v25, v30, v28
	v_mul_f32_e32 v25, v26, v25
	v_mul_f32_e32 v26, v31, v29
	v_mul_f32_e32 v26, v27, v26
	v_mul_f32_e32 v27, 0xbfb8aa3b, v20
	v_exp_f32_e32 v27, v27
	v_mul_f32_e32 v28, 0xbfb8aa3b, v21
	v_exp_f32_e32 v28, v28
	v_cvt_pk_bf16_f32 v25, v25, v26
	v_add_f32_e32 v26, 1.0, v27
	v_rcp_f32_e32 v26, v26
	v_add_f32_e32 v27, 1.0, v28
	v_rcp_f32_e32 v27, v27
	v_mad_i64_i32 v[32:33], s[26:27], v32, s55, v[144:145]
	v_lshl_add_u64 v[32:33], v[32:33], 0, s[24:25]
	v_lshl_add_u64 v[32:33], v[32:33], 0, s[12:13]
	v_mul_f32_e32 v20, v20, v26
	v_lshl_add_u64 v[32:33], v[32:33], 0, v[136:137]
	v_mul_f32_e32 v16, v16, v20
	v_mul_f32_e32 v20, v21, v27
	v_mul_f32_e32 v21, 0xbfb8aa3b, v22
	global_store_dwordx2 v[32:33], v[24:25], off
	v_exp_f32_e32 v21, v21
	v_mul_f32_e32 v24, 0xbfb8aa3b, v23
	v_exp_f32_e32 v24, v24
	v_mul_f32_e32 v17, v17, v20
	v_add_f32_e32 v20, 1.0, v21
	v_rcp_f32_e32 v20, v20
	v_add_f32_e32 v21, 1.0, v24
	v_rcp_f32_e32 v21, v21
	v_cvt_pk_bf16_f32 v16, v16, v17
	v_mul_f32_e32 v17, v22, v20
	v_mul_f32_e32 v17, v18, v17
	v_mul_f32_e32 v18, v23, v21
	v_mul_f32_e32 v18, v19, v18
	v_cvt_pk_bf16_f32 v17, v17, v18
	v_mul_f32_e32 v18, 0xbfb8aa3b, v12
	v_exp_f32_e32 v18, v18
	v_mul_f32_e32 v19, 0xbfb8aa3b, v13
	v_exp_f32_e32 v19, v19
	global_store_dwordx2 v[32:33], v[16:17], off offset:128
	v_add_f32_e32 v18, 1.0, v18
	v_rcp_f32_e32 v18, v18
	v_add_f32_e32 v19, 1.0, v19
	v_rcp_f32_e32 v19, v19
	v_add_u32_e32 v16, 0xb0, v151
	v_mul_f32_e32 v12, v12, v18
	v_mul_f32_e32 v8, v8, v12
	v_mul_f32_e32 v12, v13, v19
	v_mul_f32_e32 v13, 0xbfb8aa3b, v14
	v_exp_f32_e32 v13, v13
	v_mul_f32_e32 v18, 0xbfb8aa3b, v15
	v_exp_f32_e32 v18, v18
	v_mul_f32_e32 v9, v9, v12
	v_add_f32_e32 v12, 1.0, v13
	v_rcp_f32_e32 v12, v12
	v_add_f32_e32 v13, 1.0, v18
	v_rcp_f32_e32 v13, v13
	v_cvt_pk_bf16_f32 v8, v8, v9
	v_mul_f32_e32 v9, v14, v12
	v_mul_f32_e32 v9, v10, v9
	v_mul_f32_e32 v10, v15, v13
	v_mul_f32_e32 v10, v11, v10
	v_mul_f32_e32 v11, 0xbfb8aa3b, v4
	v_exp_f32_e32 v11, v11
	v_mul_f32_e32 v12, 0xbfb8aa3b, v5
	v_exp_f32_e32 v12, v12
	v_cvt_pk_bf16_f32 v9, v9, v10
	v_add_f32_e32 v10, 1.0, v11
	v_rcp_f32_e32 v10, v10
	v_add_f32_e32 v11, 1.0, v12
	v_rcp_f32_e32 v11, v11
	v_mad_i64_i32 v[16:17], s[26:27], v16, s55, v[144:145]
	v_lshl_add_u64 v[16:17], v[16:17], 0, s[24:25]
	v_lshl_add_u64 v[16:17], v[16:17], 0, s[12:13]
	v_mul_f32_e32 v4, v4, v10
	v_lshl_add_u64 v[16:17], v[16:17], 0, v[136:137]
	v_mul_f32_e32 v0, v0, v4
	v_mul_f32_e32 v4, v5, v11
	v_mul_f32_e32 v5, 0xbfb8aa3b, v6
	global_store_dwordx2 v[16:17], v[8:9], off
	v_exp_f32_e32 v5, v5
	v_mul_f32_e32 v8, 0xbfb8aa3b, v7
	v_exp_f32_e32 v8, v8
	v_mul_f32_e32 v1, v1, v4
	v_add_f32_e32 v4, 1.0, v5
	v_rcp_f32_e32 v4, v4
	v_add_f32_e32 v5, 1.0, v8
	v_rcp_f32_e32 v5, v5
	v_cvt_pk_bf16_f32 v0, v0, v1
	v_mul_f32_e32 v1, v6, v4
	v_mul_f32_e32 v1, v2, v1
	v_mul_f32_e32 v2, v7, v5
	s_and_b64 vcc, exec, s[18:19]
	s_mov_b32 s13, s16
	s_mov_b32 s24, s14
	s_mov_b64 s[28:29], s[22:23]
	s_mov_b64 s[26:27], s[20:21]
	v_mul_f32_e32 v2, v3, v2
	v_cvt_pk_bf16_f32 v1, v1, v2
	global_store_dwordx2 v[16:17], v[0:1], off offset:128
	s_cbranch_vccz .LBB0_1062
	s_waitcnt vmcnt(0)
	s_cmpk_gt_u32 s2, 0xff
	s_cbranch_scc1 .LBB0_1069
	s_barrier
